# stack2 plus barrier L1 invalidate issued right after the arrival atomic returns (overlaps the poll / write-back) instead of after the release
# speedup vs baseline: 1.0128x; 1.0063x over previous
.LBB0_80:
	s_or_b64 exec, exec, s[12:13]
	v_cvt_f32_u32_e32 v5, v3
	s_waitcnt vmcnt(0)
	v_readfirstlane_b32 s10, v4
	buffer_inv sc1
	s_add_u32 s8, s8, 0x2400
	s_addc_u32 s9, s9, 0
	v_rcp_iflag_f32_e32 v5, v5
	v_add_u32_e32 v6, s10, v2
	v_mul_f32_e32 v4, 0x4f7ffffe, v5
	v_cvt_u32_f32_e32 v4, v4
	v_sub_u32_e32 v5, 0, v3
	v_mul_lo_u32 v2, v5, v4
	v_mul_hi_u32 v2, v4, v2
	v_add_u32_e32 v2, v4, v2
	v_mul_hi_u32 v2, v6, v2
	v_mul_lo_u32 v4, v2, v3
	v_sub_u32_e32 v4, v6, v4
	v_add_u32_e32 v5, 1, v2
	v_cmp_ge_u32_e32 vcc, v4, v3
	s_nop 1
	v_cndmask_b32_e32 v2, v2, v5, vcc
	v_sub_u32_e32 v5, v4, v3
	v_cndmask_b32_e32 v4, v4, v5, vcc
	v_add_u32_e32 v5, 1, v2
	v_cmp_ge_u32_e32 vcc, v4, v3
	v_add_u32_e32 v4, 1, v6
	s_nop 0
	v_cndmask_b32_e32 v2, v2, v5, vcc
	v_mul_lo_u32 v5, v3, v2
	v_add_u32_e32 v3, v5, v3
	v_cmp_ne_u32_e32 vcc, v4, v3
	s_and_saveexec_b64 s[10:11], vcc
	s_xor_b64 s[10:11], exec, s[10:11]
	s_cbranch_execz .LBB0_94
	s_waitcnt lgkmcnt(0)
	v_mov_b32_e32 v1, 0
	global_load_dword v3, v1, s[8:9] sc1
	s_waitcnt vmcnt(0)
	v_cmp_eq_u32_e32 vcc, v3, v2
	s_and_saveexec_b64 s[12:13], vcc
	s_cbranch_execz .LBB0_93
	s_mov_b32 s24, 1
	s_mov_b64 s[14:15], 0
	s_branch .LBB0_84

.LBB0_93:
	s_or_b64 exec, exec, s[12:13]
	s_waitcnt vmcnt(0)
	s_waitcnt vmcnt(0)

.LBB0_111:
	s_or_b64 exec, exec, s[6:7]
	s_mov_b64 s[6:7], exec
	v_mbcnt_lo_u32_b32 v1, s6, 0
	v_mbcnt_hi_u32_b32 v1, s7, v1
	v_cmp_eq_u32_e32 vcc, 0, v1
	s_waitcnt vmcnt(0)
	s_and_saveexec_b64 s[10:11], vcc
	s_cbranch_execz .LBB0_113
	s_bcnt1_i32_b64 s6, s[6:7]
	v_mov_b32_e32 v1, 0
	v_mov_b32_e32 v2, s6
	global_atomic_add v1, v2, s[8:9]

.LBB0_1377:
	s_or_b64 exec, exec, s[12:13]
	v_cvt_f32_u32_e32 v5, v3
	s_waitcnt vmcnt(0)
	v_readfirstlane_b32 s10, v4
	buffer_inv sc1
	s_add_u32 s8, s8, 0x2400
	s_addc_u32 s9, s9, 0
	v_rcp_iflag_f32_e32 v5, v5
	v_add_u32_e32 v6, s10, v2
	v_mul_f32_e32 v4, 0x4f7ffffe, v5
	v_cvt_u32_f32_e32 v4, v4
	v_sub_u32_e32 v5, 0, v3
	v_mul_lo_u32 v2, v5, v4
	v_mul_hi_u32 v2, v4, v2
	v_add_u32_e32 v2, v4, v2
	v_mul_hi_u32 v2, v6, v2
	v_mul_lo_u32 v4, v2, v3
	v_sub_u32_e32 v4, v6, v4
	v_add_u32_e32 v5, 1, v2
	v_cmp_ge_u32_e32 vcc, v4, v3
	s_nop 1
	v_cndmask_b32_e32 v2, v2, v5, vcc
	v_sub_u32_e32 v5, v4, v3
	v_cndmask_b32_e32 v4, v4, v5, vcc
	v_add_u32_e32 v5, 1, v2
	v_cmp_ge_u32_e32 vcc, v4, v3
	v_add_u32_e32 v4, 1, v6
	s_nop 0
	v_cndmask_b32_e32 v2, v2, v5, vcc
	v_mul_lo_u32 v5, v3, v2
	v_add_u32_e32 v3, v5, v3
	v_cmp_ne_u32_e32 vcc, v4, v3
	s_and_saveexec_b64 s[10:11], vcc
	s_xor_b64 s[10:11], exec, s[10:11]
	s_cbranch_execz .LBB0_1391
	s_waitcnt lgkmcnt(0)
	v_mov_b32_e32 v1, 0
	global_load_dword v3, v1, s[8:9] sc1
	s_waitcnt vmcnt(0)
	v_cmp_eq_u32_e32 vcc, v3, v2
	s_and_saveexec_b64 s[12:13], vcc
	s_cbranch_execz .LBB0_1390
	s_mov_b32 s26, 1
	s_mov_b64 s[14:15], 0
	s_branch .LBB0_1381

.LBB0_2252:
	s_or_b64 exec, exec, s[10:11]
	v_cvt_f32_u32_e32 v5, v3
	s_waitcnt vmcnt(0)
	v_readfirstlane_b32 s8, v4
	buffer_inv sc1
	s_add_u32 s6, s6, 0x2400
	s_addc_u32 s7, s7, 0
	v_rcp_iflag_f32_e32 v5, v5
	v_add_u32_e32 v6, s8, v2
	v_mul_f32_e32 v4, 0x4f7ffffe, v5
	v_cvt_u32_f32_e32 v4, v4
	v_sub_u32_e32 v5, 0, v3
	v_mul_lo_u32 v2, v5, v4
	v_mul_hi_u32 v2, v4, v2
	v_add_u32_e32 v2, v4, v2
	v_mul_hi_u32 v2, v6, v2
	v_mul_lo_u32 v4, v2, v3
	v_sub_u32_e32 v4, v6, v4
	v_add_u32_e32 v5, 1, v2
	v_cmp_ge_u32_e32 vcc, v4, v3
	s_nop 1
	v_cndmask_b32_e32 v2, v2, v5, vcc
	v_sub_u32_e32 v5, v4, v3
	v_cndmask_b32_e32 v4, v4, v5, vcc
	v_add_u32_e32 v5, 1, v2
	v_cmp_ge_u32_e32 vcc, v4, v3
	v_add_u32_e32 v4, 1, v6
	s_nop 0
	v_cndmask_b32_e32 v2, v2, v5, vcc
	v_mul_lo_u32 v5, v3, v2
	v_add_u32_e32 v3, v5, v3
	v_cmp_ne_u32_e32 vcc, v4, v3
	s_and_saveexec_b64 s[8:9], vcc
	s_xor_b64 s[8:9], exec, s[8:9]
	s_cbranch_execz .LBB0_2266
	s_waitcnt lgkmcnt(0)
	v_mov_b32_e32 v1, 0
	global_load_dword v3, v1, s[6:7] sc1
	s_waitcnt vmcnt(0)
	v_cmp_eq_u32_e32 vcc, v3, v2
	s_and_saveexec_b64 s[10:11], vcc
	s_cbranch_execz .LBB0_2265
	s_mov_b32 s24, 1
	s_mov_b64 s[12:13], 0
	s_branch .LBB0_2256

.LBB0_2265:
	s_or_b64 exec, exec, s[10:11]
	s_waitcnt vmcnt(0)
	s_waitcnt vmcnt(0)

.LBB0_2283:
	s_or_b64 exec, exec, s[4:5]
	s_mov_b64 s[4:5], exec
	v_mbcnt_lo_u32_b32 v1, s4, 0
	v_mbcnt_hi_u32_b32 v1, s5, v1
	v_cmp_eq_u32_e32 vcc, 0, v1
	s_waitcnt vmcnt(0)
	s_and_saveexec_b64 s[8:9], vcc
	s_cbranch_execz .LBB0_2285
	s_bcnt1_i32_b64 s4, s[4:5]
	v_mov_b32_e32 v1, 0
	v_mov_b32_e32 v2, s4
	global_atomic_add v1, v2, s[6:7]

.LBB0_3169:
	s_or_b64 exec, exec, s[10:11]
	v_cvt_f32_u32_e32 v5, v3
	s_waitcnt vmcnt(0)
	v_readfirstlane_b32 s8, v4
	buffer_inv sc1
	s_add_u32 s6, s6, 0x2400
	s_addc_u32 s7, s7, 0
	v_rcp_iflag_f32_e32 v5, v5
	v_add_u32_e32 v6, s8, v2
	v_mul_f32_e32 v4, 0x4f7ffffe, v5
	v_cvt_u32_f32_e32 v4, v4
	v_sub_u32_e32 v5, 0, v3
	v_mul_lo_u32 v2, v5, v4
	v_mul_hi_u32 v2, v4, v2
	v_add_u32_e32 v2, v4, v2
	v_mul_hi_u32 v2, v6, v2
	v_mul_lo_u32 v4, v2, v3
	v_sub_u32_e32 v4, v6, v4
	v_add_u32_e32 v5, 1, v2
	v_cmp_ge_u32_e32 vcc, v4, v3
	s_nop 1
	v_cndmask_b32_e32 v2, v2, v5, vcc
	v_sub_u32_e32 v5, v4, v3
	v_cndmask_b32_e32 v4, v4, v5, vcc
	v_add_u32_e32 v5, 1, v2
	v_cmp_ge_u32_e32 vcc, v4, v3
	v_add_u32_e32 v4, 1, v6
	s_nop 0
	v_cndmask_b32_e32 v2, v2, v5, vcc
	v_mul_lo_u32 v5, v3, v2
	v_add_u32_e32 v3, v5, v3
	v_cmp_ne_u32_e32 vcc, v4, v3
	s_and_saveexec_b64 s[8:9], vcc
	s_xor_b64 s[8:9], exec, s[8:9]
	s_cbranch_execz .LBB0_3183
	s_waitcnt lgkmcnt(0)
	v_mov_b32_e32 v1, 0
	global_load_dword v3, v1, s[6:7] sc1
	s_waitcnt vmcnt(0)
	v_cmp_eq_u32_e32 vcc, v3, v2
	s_and_saveexec_b64 s[10:11], vcc
	s_cbranch_execz .LBB0_3182
	s_mov_b32 s22, 1
	s_mov_b64 s[12:13], 0
	s_branch .LBB0_3173

.LBB0_3424:
	s_or_b64 exec, exec, s[10:11]
	v_cvt_f32_u32_e32 v5, v3
	s_waitcnt vmcnt(0)
	v_readfirstlane_b32 s3, v4
	buffer_inv sc1
	s_add_u32 s6, s6, 0x2400
	s_addc_u32 s7, s7, 0
	v_rcp_iflag_f32_e32 v5, v5
	v_add_u32_e32 v6, s3, v2
	v_mul_f32_e32 v4, 0x4f7ffffe, v5
	v_cvt_u32_f32_e32 v4, v4
	v_sub_u32_e32 v5, 0, v3
	v_mul_lo_u32 v2, v5, v4
	v_mul_hi_u32 v2, v4, v2
	v_add_u32_e32 v2, v4, v2
	v_mul_hi_u32 v2, v6, v2
	v_mul_lo_u32 v4, v2, v3
	v_sub_u32_e32 v4, v6, v4
	v_add_u32_e32 v5, 1, v2
	v_cmp_ge_u32_e32 vcc, v4, v3
	s_nop 1
	v_cndmask_b32_e32 v2, v2, v5, vcc
	v_sub_u32_e32 v5, v4, v3
	v_cndmask_b32_e32 v4, v4, v5, vcc
	v_add_u32_e32 v5, 1, v2
	v_cmp_ge_u32_e32 vcc, v4, v3
	v_add_u32_e32 v4, 1, v6
	s_nop 0
	v_cndmask_b32_e32 v2, v2, v5, vcc
	v_mul_lo_u32 v5, v3, v2
	v_add_u32_e32 v3, v5, v3
	v_cmp_ne_u32_e32 vcc, v4, v3
	s_and_saveexec_b64 s[8:9], vcc
	s_xor_b64 s[8:9], exec, s[8:9]
	s_cbranch_execz .LBB0_3438
	s_waitcnt lgkmcnt(0)
	v_mov_b32_e32 v1, 0
	global_load_dword v3, v1, s[6:7] sc1
	s_waitcnt vmcnt(0)
	v_cmp_eq_u32_e32 vcc, v3, v2
	s_and_saveexec_b64 s[10:11], vcc
	s_cbranch_execz .LBB0_3437
	s_mov_b32 s3, 1
	s_mov_b64 s[12:13], 0
	s_branch .LBB0_3428

.LBB0_3455:
	s_or_b64 exec, exec, s[4:5]
	s_mov_b64 s[4:5], exec
	v_mbcnt_lo_u32_b32 v1, s4, 0
	v_mbcnt_hi_u32_b32 v1, s5, v1
	v_cmp_eq_u32_e32 vcc, 0, v1
	s_waitcnt vmcnt(0)
	s_and_saveexec_b64 s[8:9], vcc
	s_cbranch_execz .LBB0_3457
	s_bcnt1_i32_b64 s3, s[4:5]
	v_mov_b32_e32 v1, 0
	v_mov_b32_e32 v2, s3
	global_atomic_add v1, v2, s[6:7]

.LBB0_3522:
	s_or_b64 exec, exec, s[8:9]
	v_cvt_f32_u32_e32 v5, v3
	s_waitcnt vmcnt(0)
	v_readfirstlane_b32 s6, v4
	buffer_inv sc1
	s_add_u32 s4, s4, 0x2400
	s_addc_u32 s5, s5, 0
	v_rcp_iflag_f32_e32 v5, v5
	v_add_u32_e32 v6, s6, v2
	v_mul_f32_e32 v4, 0x4f7ffffe, v5
	v_cvt_u32_f32_e32 v4, v4
	v_sub_u32_e32 v5, 0, v3
	v_mul_lo_u32 v2, v5, v4
	v_mul_hi_u32 v2, v4, v2
	v_add_u32_e32 v2, v4, v2
	v_mul_hi_u32 v2, v6, v2
	v_mul_lo_u32 v4, v2, v3
	v_sub_u32_e32 v4, v6, v4
	v_add_u32_e32 v5, 1, v2
	v_cmp_ge_u32_e32 vcc, v4, v3
	s_nop 1
	v_cndmask_b32_e32 v2, v2, v5, vcc
	v_sub_u32_e32 v5, v4, v3
	v_cndmask_b32_e32 v4, v4, v5, vcc
	v_add_u32_e32 v5, 1, v2
	v_cmp_ge_u32_e32 vcc, v4, v3
	v_add_u32_e32 v4, 1, v6
	s_nop 0
	v_cndmask_b32_e32 v2, v2, v5, vcc
	v_mul_lo_u32 v5, v3, v2
	v_add_u32_e32 v3, v5, v3
	v_cmp_ne_u32_e32 vcc, v4, v3
	s_and_saveexec_b64 s[6:7], vcc
	s_xor_b64 s[6:7], exec, s[6:7]
	s_cbranch_execz .LBB0_3536
	s_waitcnt lgkmcnt(0)
	v_mov_b32_e32 v1, 0
	global_load_dword v3, v1, s[4:5] sc1
	s_waitcnt vmcnt(0)
	v_cmp_eq_u32_e32 vcc, v3, v2
	s_and_saveexec_b64 s[8:9], vcc
	s_cbranch_execz .LBB0_3535
	s_mov_b32 s20, 1
	s_mov_b64 s[10:11], 0
	s_branch .LBB0_3526

.LBB0_3535:
	s_or_b64 exec, exec, s[8:9]
	s_waitcnt vmcnt(0)
	s_waitcnt vmcnt(0)

.LBB0_3553:
	s_or_b64 exec, exec, s[2:3]
	s_mov_b64 s[2:3], exec
	v_mbcnt_lo_u32_b32 v1, s2, 0
	v_mbcnt_hi_u32_b32 v1, s3, v1
	v_cmp_eq_u32_e32 vcc, 0, v1
	s_waitcnt vmcnt(0)
	s_and_saveexec_b64 s[6:7], vcc
	s_cbranch_execz .LBB0_3555
	s_bcnt1_i32_b64 s2, s[2:3]
	v_mov_b32_e32 v1, 0
	v_mov_b32_e32 v2, s2
	global_atomic_add v1, v2, s[4:5]

.LBB0_3592:
	s_or_b64 exec, exec, s[8:9]
	v_cvt_f32_u32_e32 v4, v2
	s_waitcnt vmcnt(0)
	v_readfirstlane_b32 s6, v3
	buffer_inv sc1
	s_add_u32 s4, s4, 0x2400
	s_addc_u32 s5, s5, 0
	v_rcp_iflag_f32_e32 v4, v4
	v_add_u32_e32 v5, s6, v1
	v_mul_f32_e32 v3, 0x4f7ffffe, v4
	v_cvt_u32_f32_e32 v3, v3
	v_sub_u32_e32 v4, 0, v2
	v_mul_lo_u32 v1, v4, v3
	v_mul_hi_u32 v1, v3, v1
	v_add_u32_e32 v1, v3, v1
	v_mul_hi_u32 v1, v5, v1
	v_mul_lo_u32 v3, v1, v2
	v_sub_u32_e32 v3, v5, v3
	v_add_u32_e32 v4, 1, v1
	v_cmp_ge_u32_e32 vcc, v3, v2
	s_nop 1
	v_cndmask_b32_e32 v1, v1, v4, vcc
	v_sub_u32_e32 v4, v3, v2
	v_cndmask_b32_e32 v3, v3, v4, vcc
	v_add_u32_e32 v4, 1, v1
	v_cmp_ge_u32_e32 vcc, v3, v2
	v_add_u32_e32 v3, 1, v5
	s_nop 0
	v_cndmask_b32_e32 v1, v1, v4, vcc
	v_mul_lo_u32 v4, v2, v1
	v_add_u32_e32 v2, v4, v2
	v_cmp_ne_u32_e32 vcc, v3, v2
	s_and_saveexec_b64 s[6:7], vcc
	s_xor_b64 s[6:7], exec, s[6:7]
	s_cbranch_execz .LBB0_3606
	s_waitcnt lgkmcnt(0)
	v_mov_b32_e32 v0, 0
	global_load_dword v2, v0, s[4:5] sc1
	s_waitcnt vmcnt(0)
	v_cmp_eq_u32_e32 vcc, v2, v1
	s_and_saveexec_b64 s[8:9], vcc
	s_cbranch_execz .LBB0_3605
	s_mov_b32 s20, 1
	s_mov_b64 s[10:11], 0
	s_branch .LBB0_3596

.LBB0_3623:
	s_or_b64 exec, exec, s[2:3]
	s_mov_b64 s[2:3], exec
	v_mbcnt_lo_u32_b32 v0, s2, 0
	v_mbcnt_hi_u32_b32 v0, s3, v0
	v_cmp_eq_u32_e32 vcc, 0, v0
	s_waitcnt vmcnt(0)
	s_and_saveexec_b64 s[6:7], vcc
	s_cbranch_execz .LBB0_3625
	s_bcnt1_i32_b64 s2, s[2:3]
	v_mov_b32_e32 v0, 0
	v_mov_b32_e32 v1, s2
	global_atomic_add v0, v1, s[4:5]
